# grid barrier: L1 invalidate issued early (before polling / with the XCD leader's L2 write-back) instead of after release
# speedup vs baseline: 1.0313x; 1.0013x over previous
.LBB0_76:
	s_or_b64 exec, exec, s[18:19]
	v_cvt_f32_u32_e32 v6, v4
	s_waitcnt vmcnt(0)
	v_readfirstlane_b32 s3, v5
	v_sub_u32_e32 v5, 0, v4
	v_rcp_iflag_f32_e32 v6, v6
	v_add_u32_e32 v7, s3, v3
	v_mul_f32_e32 v6, 0x4f7ffffe, v6
	v_cvt_u32_f32_e32 v6, v6
	v_mul_lo_u32 v3, v5, v6
	v_mul_hi_u32 v3, v6, v3
	v_add_u32_e32 v3, v6, v3
	v_mul_hi_u32 v3, v7, v3
	v_mul_lo_u32 v5, v3, v4
	v_sub_u32_e32 v5, v7, v5
	v_add_u32_e32 v6, 1, v3
	v_cmp_ge_u32_e32 vcc, v5, v4
	s_nop 1
	v_cndmask_b32_e32 v3, v3, v6, vcc
	v_sub_u32_e32 v6, v5, v4
	v_cndmask_b32_e32 v5, v5, v6, vcc
	v_add_u32_e32 v6, 1, v3
	v_cmp_ge_u32_e32 vcc, v5, v4
	v_add_u32_e32 v5, 1, v7
	s_nop 0
	v_cndmask_b32_e32 v3, v3, v6, vcc
	v_mul_lo_u32 v6, v4, v3
	v_add_u32_e32 v4, v6, v4
	v_cmp_ne_u32_e32 vcc, v5, v4
	s_and_saveexec_b64 s[4:5], vcc
	s_xor_b64 s[12:13], exec, s[4:5]
	s_cbranch_execz .LBB0_90
	s_waitcnt lgkmcnt(0)
	v_mov_b32_e32 v2, 0x2000
	buffer_inv sc1
	global_load_dword v2, v2, s[10:11] offset:1024 sc1
	s_add_u32 s22, s10, 0x2400
	s_addc_u32 s23, s11, 0
	s_waitcnt vmcnt(0)
	v_cmp_eq_u32_e32 vcc, v2, v3
	s_and_saveexec_b64 s[18:19], vcc
	s_cbranch_execz .LBB0_89
	s_add_u32 s20, s8, 0x17200200
	s_addc_u32 s21, s9, 0
	s_mov_b32 s3, 1
	s_mov_b64 s[24:25], 0
	v_mov_b32_e32 v2, 0
	s_branch .LBB0_80

.LBB0_89:
	s_or_b64 exec, exec, s[18:19]
	s_waitcnt vmcnt(0)
	s_waitcnt vmcnt(0)
.LBB0_90:
	s_andn2_saveexec_b64 s[4:5], s[12:13]
	s_cbranch_execz .LBB0_110
	s_mov_b64 s[12:13], exec
	buffer_wbl2 sc1
	buffer_inv sc1
	s_waitcnt lgkmcnt(0)
	s_waitcnt vmcnt(0)
	v_mbcnt_lo_u32_b32 v3, s12, 0
	v_mbcnt_hi_u32_b32 v3, s13, v3
	v_cmp_eq_u32_e32 vcc, 0, v3
	s_and_saveexec_b64 s[18:19], vcc
	s_cbranch_execz .LBB0_93
	s_bcnt1_i32_b64 s3, s[12:13]
	v_mov_b32_e32 v4, 0x17203000
	v_mov_b32_e32 v5, s3
	global_atomic_add v4, v4, v5, s[8:9] offset:1024 sc0

.LBB0_107:
	s_or_b64 exec, exec, s[8:9]
	s_mov_b64 s[8:9], exec
	v_mbcnt_lo_u32_b32 v2, s8, 0
	v_mbcnt_hi_u32_b32 v2, s9, v2
	v_cmp_eq_u32_e32 vcc, 0, v2
	s_waitcnt vmcnt(0)
	s_and_saveexec_b64 s[12:13], vcc
	s_cbranch_execz .LBB0_109
	s_bcnt1_i32_b64 s3, s[8:9]
	v_mov_b32_e32 v2, 0x2000
	v_mov_b32_e32 v3, s3
	global_atomic_add v2, v3, s[10:11] offset:1024

.LBB0_446:
	s_or_b64 exec, exec, s[22:23]
	v_cvt_f32_u32_e32 v6, v4
	s_waitcnt vmcnt(0)
	v_readfirstlane_b32 s4, v5
	v_sub_u32_e32 v5, 0, v4
	v_rcp_iflag_f32_e32 v6, v6
	v_add_u32_e32 v7, s4, v3
	v_mul_f32_e32 v6, 0x4f7ffffe, v6
	v_cvt_u32_f32_e32 v6, v6
	v_mul_lo_u32 v3, v5, v6
	v_mul_hi_u32 v3, v6, v3
	v_add_u32_e32 v3, v6, v3
	v_mul_hi_u32 v3, v7, v3
	v_mul_lo_u32 v5, v3, v4
	v_sub_u32_e32 v5, v7, v5
	v_add_u32_e32 v6, 1, v3
	v_cmp_ge_u32_e32 vcc, v5, v4
	s_nop 1
	v_cndmask_b32_e32 v3, v3, v6, vcc
	v_sub_u32_e32 v6, v5, v4
	v_cndmask_b32_e32 v5, v5, v6, vcc
	v_add_u32_e32 v6, 1, v3
	v_cmp_ge_u32_e32 vcc, v5, v4
	v_add_u32_e32 v5, 1, v7
	s_nop 0
	v_cndmask_b32_e32 v3, v3, v6, vcc
	v_mul_lo_u32 v6, v4, v3
	v_add_u32_e32 v4, v6, v4
	v_cmp_ne_u32_e32 vcc, v5, v4
	s_and_saveexec_b64 s[4:5], vcc
	s_xor_b64 s[12:13], exec, s[4:5]
	s_cbranch_execz .LBB0_460
	s_waitcnt lgkmcnt(0)
	buffer_inv sc1
	global_load_dword v2, v168, s[10:11] offset:1024 sc1
	s_add_u32 s44, s10, 0x2400
	s_addc_u32 s45, s11, 0
	s_waitcnt vmcnt(0)
	v_cmp_eq_u32_e32 vcc, v2, v3
	s_and_saveexec_b64 s[22:23], vcc
	s_cbranch_execz .LBB0_459
	s_add_u32 s26, s8, 0x17200200
	s_addc_u32 s27, s9, 0
	s_mov_b32 s4, 1
	s_mov_b64 s[46:47], 0
	s_branch .LBB0_450

.LBB0_459:
	s_or_b64 exec, exec, s[22:23]
	s_waitcnt vmcnt(0)
	s_waitcnt vmcnt(0)
.LBB0_460:
	s_andn2_saveexec_b64 s[4:5], s[12:13]
	s_cbranch_execz .LBB0_112
	s_mov_b64 s[12:13], exec
	buffer_wbl2 sc1
	buffer_inv sc1
	s_waitcnt lgkmcnt(0)
	s_waitcnt vmcnt(0)
	v_mbcnt_lo_u32_b32 v3, s12, 0
	v_mbcnt_hi_u32_b32 v3, s13, v3
	v_cmp_eq_u32_e32 vcc, 0, v3
	s_and_saveexec_b64 s[22:23], vcc
	s_cbranch_execz .LBB0_463
	s_bcnt1_i32_b64 s4, s[12:13]
	v_mov_b32_e32 v4, s4
	v_mov_b32_e32 v5, 0x17203000
	global_atomic_add v4, v5, v4, s[8:9] offset:1024 sc0

.LBB0_477:
	s_or_b64 exec, exec, s[8:9]
	s_mov_b64 s[8:9], exec
	v_mbcnt_lo_u32_b32 v2, s8, 0
	v_mbcnt_hi_u32_b32 v2, s9, v2
	v_cmp_eq_u32_e32 vcc, 0, v2
	s_waitcnt vmcnt(0)
	s_and_saveexec_b64 s[12:13], vcc
	s_cbranch_execz .LBB0_111
	s_bcnt1_i32_b64 s4, s[8:9]
	v_mov_b32_e32 v2, s4
	global_atomic_add v168, v2, s[10:11] offset:1024
	s_branch .LBB0_111
